# K-loop: per-segment s_setprio toggles replaced by one static priority raise for the second wave half (wr=1) per unit
# speedup vs baseline: 1.0009x; 1.0009x over previous
; #define PG8_LDA(dst, b, h) do { _Pragma("unroll") for (int m = 0; m < 4; ++m) _Pragma("unroll") for (int k = 0; k < 2; ++k) dst[m][k] = *(const LAS bf16x8*)(lds + PG8_SA(b, h) + aoff + m * 2048 + k * 1024); } while (0)
; #define PG8_LDB(dst, b, h) do { _Pragma("unroll") for (int n = 0; n < 2; ++n) _Pragma("unroll") for (int k = 0; k < 2; ++k) dst[n][k] = *(const LAS bf16x8*)(lds + PG8_SB(b, h) + boff + n * 2048 + k * 1024); } while (0)
; #define PG8_MMA(ai, bj, At, Bt) do { __builtin_amdgcn_s_setprio(1); _Pragma("unroll") for (int m = 0; m < 4; ++m) _Pragma("unroll") for (int n = 0; n < 2; ++n) _Pragma("unroll") for (int k = 0; k < 2; ++k) \
;         acc[ai][bj][m][n] = __builtin_amdgcn_mfma_f32_16x16x32_bf16(Bt[n][k], At[m][k], acc[ai][bj][m][n], 0, 0, 0); __builtin_amdgcn_s_setprio(0); } while (0)
; #define PG8_WAIT_V(n) asm volatile("s_waitcnt vmcnt(" #n ")" ::: "memory")
; #define PG8_WAIT_L(n) asm volatile("s_waitcnt lgkmcnt(" #n ")" ::: "memory")
; #define PG8_BAR __builtin_amdgcn_s_barrier()
; #define PG8_SCHED __builtin_amdgcn_sched_barrier(0)
; #define PG8_STA(bufoff, gbase, ld) PG8_STAGE(bufoff, gbase, RA0 * (unsigned)(ld) + CC0, RA1 * (unsigned)(ld) + CC1)
; __device__ __forceinline__ void gemm_phase(LAS unsigned char* lds, const Sched& S, const Epi& E) {
;     ...
;     for (int a = 0; a < 2; ++a)
; #pragma unroll
;         for (int b = 0; b < 2; ++b)
; #pragma unroll
;             for (int m = 0; m < 4; ++m)
; #pragma unroll
;                 for (int n = 0; n < 2; ++n) acc[a][b][m][n] = (f32x4){0.f, 0.f, 0.f, 0.f};
;     ...
;         for (int t = 0; t < nt_main; t += 2) {
;             const bool last = (t == nt - 2);
;             const char* a1 = cA + (size_t)(t + 1) * kstep;
;             const char* a2 = last ? nA : cA + (size_t)(t + 2) * kstep; const char* b2 = last ? nB : cB + (size_t)(t + 2) * kstep;
;             const char* a3 = a2 + kstep; const char* b3 = b2 + kstep;
;             const int xlda = last ? nlda : lda, xldb = last ? nldb : ldb;
;             const size_t xhA = (size_t)HALF * xlda * 2, xhB = (size_t)HALF * xldb * 2;
;             PG8_LDB(B0, 0, 0); PG8_LDB(B1, 0, 1); PG8_SCHED; PG8_LDA(At, 0, 0); PG8_STA(PG8_SA(1, 1), a1 + hA, lda);
;             PG8_WAIT_V(8); PG8_WAIT_L(0); PG8_BAR; PG8_MMA(0, 0, At, B0); PG8_MMA(0, 1, At, B1); PG8_BAR; PG8_SCHED;
.LBB0_261:
	s_mov_b32 s21, s31
	s_lshl_b64 s[66:67], s[20:21], 8
	s_add_i32 s21, s60, -2
	s_and_b64 s[26:27], s[42:43], exec
	s_cselect_b32 s68, s60, s21
	s_cmp_lt_i32 s68, 1
	s_cbranch_scc1 .LBB0_274
	s_add_u32 vcc_lo, s96, 0x80
	s_addc_u32 vcc_hi, s97, 0
	s_add_u32 s2, s8, 0x100
	s_addc_u32 s72, s9, 0
	v_mad_u64_u32 v[2:3], s[8:9], s20, v235, v[206:207]
	v_mov_b32_e32 v3, v1
	s_waitcnt lgkmcnt(0)
	v_lshl_add_u64 v[130:131], s[66:67], 0, v[2:3]
	v_mad_u64_u32 v[2:3], s[8:9], s20, v236, v[208:209]
	v_mov_b32_e32 v3, v1
	v_lshl_add_u64 v[132:133], s[66:67], 0, v[2:3]
	s_mov_b32 s3, s92
	s_mov_b32 s8, 0
	v_mov_b64_e32 v[2:3], 0
	v_mov_b64_e32 v[4:5], 0
	v_mov_b64_e32 v[6:7], 0
	v_mov_b64_e32 v[8:9], 0
	v_mov_b64_e32 v[10:11], 0
	v_mov_b64_e32 v[12:13], 0
	v_mov_b64_e32 v[14:15], 0
	v_mov_b64_e32 v[16:17], 0
	v_mov_b64_e32 v[18:19], 0
	v_mov_b64_e32 v[20:21], 0
	v_mov_b64_e32 v[22:23], 0
	v_mov_b64_e32 v[24:25], 0
	v_mov_b64_e32 v[26:27], 0
	v_mov_b64_e32 v[28:29], 0
	v_mov_b64_e32 v[30:31], 0
	v_mov_b64_e32 v[32:33], 0
	v_mov_b64_e32 v[34:35], 0
	v_mov_b64_e32 v[36:37], 0
	v_mov_b64_e32 v[38:39], 0
	v_mov_b64_e32 v[40:41], 0
	v_mov_b64_e32 v[42:43], 0
	v_mov_b64_e32 v[44:45], 0
	v_mov_b64_e32 v[46:47], 0
	v_mov_b64_e32 v[48:49], 0
	v_mov_b64_e32 v[50:51], 0
	v_mov_b64_e32 v[52:53], 0
	v_mov_b64_e32 v[54:55], 0
	v_mov_b64_e32 v[56:57], 0
	v_mov_b64_e32 v[58:59], 0
	v_mov_b64_e32 v[60:61], 0
	v_mov_b64_e32 v[62:63], 0
	v_mov_b64_e32 v[64:65], 0
	v_mov_b64_e32 v[66:67], 0
	v_mov_b64_e32 v[68:69], 0
	v_mov_b64_e32 v[70:71], 0
	v_mov_b64_e32 v[72:73], 0
	v_mov_b64_e32 v[74:75], 0
	v_mov_b64_e32 v[76:77], 0
	v_mov_b64_e32 v[78:79], 0
	v_mov_b64_e32 v[80:81], 0
	v_mov_b64_e32 v[82:83], 0
	v_mov_b64_e32 v[84:85], 0
	v_mov_b64_e32 v[86:87], 0
	v_mov_b64_e32 v[88:89], 0
	v_mov_b64_e32 v[90:91], 0
	v_mov_b64_e32 v[92:93], 0
	v_mov_b64_e32 v[94:95], 0
	v_mov_b64_e32 v[96:97], 0
	v_mov_b64_e32 v[98:99], 0
	v_mov_b64_e32 v[100:101], 0
	v_mov_b64_e32 v[102:103], 0
	v_mov_b64_e32 v[104:105], 0
	v_mov_b64_e32 v[106:107], 0
	v_mov_b64_e32 v[108:109], 0
	v_mov_b64_e32 v[110:111], 0
	v_mov_b64_e32 v[112:113], 0
	v_mov_b64_e32 v[114:115], 0
	v_mov_b64_e32 v[116:117], 0
	v_mov_b64_e32 v[118:119], 0
	v_mov_b64_e32 v[120:121], 0
	v_mov_b64_e32 v[122:123], 0
	v_mov_b64_e32 v[124:125], 0
	v_mov_b64_e32 v[126:127], 0
	v_mov_b64_e32 v[128:129], 0
	v_readlane_b32 s24, v250, 25
	s_nop 0
	s_cmp_lg_u32 s24, 0
	s_cbranch_scc0 .Lmy_np
	s_setprio 1
.Lmy_np:
.LBB0_263:
	s_add_i32 s24, s8, 2
	s_add_u32 s26, vcc_lo, 0x80
	s_addc_u32 s9, vcc_hi, 0
	s_add_i32 s37, 0, 0x10000
	s_cmp_eq_u32 s21, s8
	s_cselect_b32 s9, s7, s9
	s_cselect_b32 s8, s6, s26
	s_cselect_b32 s92, s11, s61
	s_cselect_b32 s30, s22, s20
	v_add_u32_e32 v0, s37, v241
	s_cselect_b32 s29, s13, s72
	s_cselect_b32 s28, s12, s2
	s_add_i32 s57, 0, 0x14000
	ds_read_b128 v[134:137], v0
	ds_read_b128 v[138:141], v0 offset:1024
	ds_read_b128 v[142:145], v0 offset:2048
	ds_read_b128 v[146:149], v0 offset:3072
	v_add_u32_e32 v0, s57, v241
	ds_read_b128 v[150:153], v0
	ds_read_b128 v[154:157], v0 offset:1024
	ds_read_b128 v[158:161], v0 offset:2048
	ds_read_b128 v[162:165], v0 offset:3072
	s_mov_b32 s93, s31
	s_lshl_b64 s[26:27], s[30:31], 8
	v_add_u32_e32 v0, 0, v240
	v_lshl_add_u64 v[214:215], vcc, 0, v[130:131]
	s_add_i32 m0, s34, 0xc000
	ds_read_b128 v[166:169], v0
	ds_read_b128 v[170:173], v0 offset:1024
	ds_read_b128 v[174:177], v0 offset:2048
	ds_read_b128 v[178:181], v0 offset:3072
	ds_read_b128 v[182:185], v0 offset:4096
	ds_read_b128 v[186:189], v0 offset:5120
	ds_read_b128 v[190:193], v0 offset:6144
	ds_read_b128 v[210:213], v0 offset:7168
	global_load_lds_dwordx4 v[214:215], off
	v_lshl_add_u64 v[214:215], vcc, 0, v[132:133]
	s_add_i32 m0, s34, 0xe000
	s_nop 0
	global_load_lds_dwordx4 v[214:215], off
	s_waitcnt vmcnt(8)
	s_waitcnt lgkmcnt(0)
	s_barrier
	s_nop 0
	s_waitcnt lgkmcnt(0)
	v_mfma_f32_16x16x32_bf16 v[126:129], v[134:137], v[166:169], v[126:129]
	v_mfma_f32_16x16x32_bf16 v[122:125], v[142:145], v[166:169], v[122:125]
	v_mfma_f32_16x16x32_bf16 v[110:113], v[134:137], v[174:177], v[110:113]
	v_mfma_f32_16x16x32_bf16 v[106:109], v[142:145], v[174:177], v[106:109]
	v_mfma_f32_16x16x32_bf16 v[98:101], v[134:137], v[182:185], v[98:101]
	v_mfma_f32_16x16x32_bf16 v[90:93], v[142:145], v[182:185], v[90:93]
	v_mfma_f32_16x16x32_bf16 v[82:85], v[134:137], v[190:193], v[82:85]
	v_mfma_f32_16x16x32_bf16 v[74:77], v[142:145], v[190:193], v[74:77]
	v_mfma_f32_16x16x32_bf16 v[126:129], v[138:141], v[170:173], v[126:129]
	v_mfma_f32_16x16x32_bf16 v[122:125], v[146:149], v[170:173], v[122:125]
	v_mfma_f32_16x16x32_bf16 v[110:113], v[138:141], v[178:181], v[110:113]
	v_mfma_f32_16x16x32_bf16 v[106:109], v[146:149], v[178:181], v[106:109]
	v_mfma_f32_16x16x32_bf16 v[98:101], v[138:141], v[186:189], v[98:101]
	v_mfma_f32_16x16x32_bf16 v[90:93], v[146:149], v[186:189], v[90:93]
	v_mfma_f32_16x16x32_bf16 v[82:85], v[138:141], v[210:213], v[82:85]
	v_mfma_f32_16x16x32_bf16 v[74:77], v[146:149], v[210:213], v[74:77]
	s_nop 0
	s_nop 0
	v_mfma_f32_16x16x32_bf16 v[118:121], v[150:153], v[166:169], v[118:121]
	v_mfma_f32_16x16x32_bf16 v[114:117], v[158:161], v[166:169], v[114:117]
	v_mfma_f32_16x16x32_bf16 v[102:105], v[150:153], v[174:177], v[102:105]
	v_mfma_f32_16x16x32_bf16 v[94:97], v[158:161], v[174:177], v[94:97]
	v_mfma_f32_16x16x32_bf16 v[86:89], v[150:153], v[182:185], v[86:89]
	v_mfma_f32_16x16x32_bf16 v[78:81], v[158:161], v[182:185], v[78:81]
	v_mfma_f32_16x16x32_bf16 v[70:73], v[150:153], v[190:193], v[70:73]
	v_mfma_f32_16x16x32_bf16 v[66:69], v[158:161], v[190:193], v[66:69]
	v_mfma_f32_16x16x32_bf16 v[118:121], v[154:157], v[170:173], v[118:121]
	v_mfma_f32_16x16x32_bf16 v[114:117], v[162:165], v[170:173], v[114:117]
	v_mfma_f32_16x16x32_bf16 v[102:105], v[154:157], v[178:181], v[102:105]
	v_mfma_f32_16x16x32_bf16 v[94:97], v[162:165], v[178:181], v[94:97]
	v_mfma_f32_16x16x32_bf16 v[86:89], v[154:157], v[186:189], v[86:89]
	v_mfma_f32_16x16x32_bf16 v[78:81], v[162:165], v[186:189], v[78:81]
	v_mfma_f32_16x16x32_bf16 v[70:73], v[154:157], v[210:213], v[70:73]
	v_mfma_f32_16x16x32_bf16 v[66:69], v[162:165], v[210:213], v[66:69]
	s_nop 0
	s_barrier
; #define PG8_LDA(dst, b, h) do { _Pragma("unroll") for (int m = 0; m < 4; ++m) _Pragma("unroll") for (int k = 0; k < 2; ++k) dst[m][k] = *(const LAS bf16x8*)(lds + PG8_SA(b, h) + aoff + m * 2048 + k * 1024); } while (0)
; #define PG8_LDB(dst, b, h) do { _Pragma("unroll") for (int n = 0; n < 2; ++n) _Pragma("unroll") for (int k = 0; k < 2; ++k) dst[n][k] = *(const LAS bf16x8*)(lds + PG8_SB(b, h) + boff + n * 2048 + k * 1024); } while (0)
; #define PG8_MMA(ai, bj, At, Bt) do { __builtin_amdgcn_s_setprio(1); _Pragma("unroll") for (int m = 0; m < 4; ++m) _Pragma("unroll") for (int n = 0; n < 2; ++n) _Pragma("unroll") for (int k = 0; k < 2; ++k) \
;         acc[ai][bj][m][n] = __builtin_amdgcn_mfma_f32_16x16x32_bf16(Bt[n][k], At[m][k], acc[ai][bj][m][n], 0, 0, 0); __builtin_amdgcn_s_setprio(0); } while (0)
; #define PG8_WAIT_V(n) asm volatile("s_waitcnt vmcnt(" #n ")" ::: "memory")
; #define PG8_WAIT_L(n) asm volatile("s_waitcnt lgkmcnt(" #n ")" ::: "memory")
; #define PG8_BAR __builtin_amdgcn_s_barrier()
; #define PG8_SCHED __builtin_amdgcn_sched_barrier(0)
; #define PG8_STA(bufoff, gbase, ld) PG8_STAGE(bufoff, gbase, RA0 * (unsigned)(ld) + CC0, RA1 * (unsigned)(ld) + CC1)
; #define PG8_STB(bufoff, gbase, ld) PG8_STAGE(bufoff, gbase, RB0 * (unsigned)(ld) + CC0, RB1 * (unsigned)(ld) + CC1)
; __device__ __forceinline__ void gemm_phase(LAS unsigned char* lds, const Sched& S, const Epi& E) {
;     ...
;             PG8_LDA(At, 0, 1); PG8_STB(PG8_SB(0, 0), b2, xldb); PG8_STB(PG8_SB(0, 1), b2 + xhB, xldb); PG8_STA(PG8_SA(0, 0), a2, xlda);
;             PG8_WAIT_V(8); PG8_WAIT_L(0); PG8_BAR; PG8_MMA(1, 0, At, B0); PG8_MMA(1, 1, At, B1); PG8_BAR; PG8_SCHED;
;             PG8_LDB(B0, 1, 0); PG8_LDB(B1, 1, 1); PG8_SCHED; PG8_LDA(At, 1, 0); PG8_STA(PG8_SA(0, 1), a2 + xhA, xlda);
;             PG8_WAIT_V(8); PG8_WAIT_L(0); PG8_BAR; PG8_MMA(0, 0, At, B0); PG8_MMA(0, 1, At, B1); PG8_BAR; PG8_SCHED;
	s_add_i32 s37, s37, s25
	v_mad_u64_u32 v[214:215], s[80:81], s92, v237, v[194:195]
	s_mov_b32 m0, s37
	ds_read_b128 v[166:169], v0 offset:16384
	ds_read_b128 v[170:173], v0 offset:17408
	ds_read_b128 v[174:177], v0 offset:18432
	ds_read_b128 v[178:181], v0 offset:19456
	ds_read_b128 v[182:185], v0 offset:20480
	ds_read_b128 v[186:189], v0 offset:21504
	ds_read_b128 v[190:193], v0 offset:22528
	ds_read_b128 v[210:213], v0 offset:23552
	s_lshl_b64 s[74:75], s[92:93], 8
	global_load_lds_dwordx4 v214, s[28:29]
	s_add_i32 m0, s37, 0x2000
	s_add_u32 s74, s28, s74
	v_mad_u64_u32 v[216:217], s[80:81], s92, v238, v[196:197]
	s_addc_u32 s75, s29, s75
	s_add_i32 s37, s57, s25
	global_load_lds_dwordx4 v216, s[28:29]
	s_mov_b32 m0, s37
	v_mad_u64_u32 v[218:219], s[80:81], s30, v235, v[194:195]
	global_load_lds_dwordx4 v214, s[74:75]
	s_add_i32 m0, s37, 0x2000
	v_mad_u64_u32 v[220:221], s[80:81], s30, v236, v[196:197]
	global_load_lds_dwordx4 v216, s[74:75]
	s_mov_b32 m0, s34
	v_mov_b32_e32 v215, v1
	global_load_lds_dwordx4 v218, s[8:9]
	s_mov_b32 m0, s35
	v_mov_b32_e32 v217, v1
	global_load_lds_dwordx4 v220, s[8:9]
	v_mov_b32_e32 v219, v1
	v_mov_b32_e32 v221, v1
	v_lshl_add_u64 v[222:223], s[28:29], 0, v[214:215]
	v_lshl_add_u64 v[224:225], s[28:29], 0, v[216:217]
	v_lshl_add_u64 v[214:215], s[74:75], 0, v[214:215]
	v_lshl_add_u64 v[216:217], s[74:75], 0, v[216:217]
	v_lshl_add_u64 v[226:227], s[8:9], 0, v[218:219]
	v_lshl_add_u64 v[228:229], s[8:9], 0, v[220:221]
	s_waitcnt vmcnt(8)
	s_waitcnt lgkmcnt(0)
	s_barrier
	s_nop 0
	s_waitcnt lgkmcnt(0)
	v_mfma_f32_16x16x32_bf16 v[62:65], v[134:137], v[166:169], v[62:65]
	v_mfma_f32_16x16x32_bf16 v[58:61], v[142:145], v[166:169], v[58:61]
	v_mfma_f32_16x16x32_bf16 v[46:49], v[134:137], v[174:177], v[46:49]
	v_mfma_f32_16x16x32_bf16 v[42:45], v[142:145], v[174:177], v[42:45]
	v_mfma_f32_16x16x32_bf16 v[30:33], v[134:137], v[182:185], v[30:33]
	v_mfma_f32_16x16x32_bf16 v[26:29], v[142:145], v[182:185], v[26:29]
	v_mfma_f32_16x16x32_bf16 v[14:17], v[134:137], v[190:193], v[14:17]
	v_mfma_f32_16x16x32_bf16 v[10:13], v[142:145], v[190:193], v[10:13]
	v_mfma_f32_16x16x32_bf16 v[62:65], v[138:141], v[170:173], v[62:65]
	v_mfma_f32_16x16x32_bf16 v[58:61], v[146:149], v[170:173], v[58:61]
	v_mfma_f32_16x16x32_bf16 v[46:49], v[138:141], v[178:181], v[46:49]
	v_mfma_f32_16x16x32_bf16 v[42:45], v[146:149], v[178:181], v[42:45]
	v_mfma_f32_16x16x32_bf16 v[30:33], v[138:141], v[186:189], v[30:33]
	v_mfma_f32_16x16x32_bf16 v[26:29], v[146:149], v[186:189], v[26:29]
	v_mfma_f32_16x16x32_bf16 v[14:17], v[138:141], v[210:213], v[14:17]
	v_mfma_f32_16x16x32_bf16 v[10:13], v[146:149], v[210:213], v[10:13]
	s_nop 0
	s_nop 0
	v_mfma_f32_16x16x32_bf16 v[54:57], v[150:153], v[166:169], v[54:57]
	v_mfma_f32_16x16x32_bf16 v[50:53], v[158:161], v[166:169], v[50:53]
	v_mfma_f32_16x16x32_bf16 v[38:41], v[150:153], v[174:177], v[38:41]
	v_mfma_f32_16x16x32_bf16 v[34:37], v[158:161], v[174:177], v[34:37]
	v_mfma_f32_16x16x32_bf16 v[22:25], v[150:153], v[182:185], v[22:25]
	v_mfma_f32_16x16x32_bf16 v[18:21], v[158:161], v[182:185], v[18:21]
	v_mfma_f32_16x16x32_bf16 v[6:9], v[150:153], v[190:193], v[6:9]
	v_mfma_f32_16x16x32_bf16 v[2:5], v[158:161], v[190:193], v[2:5]
	v_mfma_f32_16x16x32_bf16 v[54:57], v[154:157], v[170:173], v[54:57]
	v_mfma_f32_16x16x32_bf16 v[50:53], v[162:165], v[170:173], v[50:53]
	v_mfma_f32_16x16x32_bf16 v[38:41], v[154:157], v[178:181], v[38:41]
	v_mfma_f32_16x16x32_bf16 v[34:37], v[162:165], v[178:181], v[34:37]
	v_mfma_f32_16x16x32_bf16 v[22:25], v[154:157], v[186:189], v[22:25]
	v_mfma_f32_16x16x32_bf16 v[18:21], v[162:165], v[186:189], v[18:21]
	v_mfma_f32_16x16x32_bf16 v[6:9], v[154:157], v[210:213], v[6:9]
	v_mfma_f32_16x16x32_bf16 v[2:5], v[162:165], v[210:213], v[2:5]
	s_nop 0
	s_barrier
	s_add_i32 s28, 0, 0x18000
	s_add_i32 s29, 0, 0x1c000
	v_add_u32_e32 v146, s28, v241
	v_add_u32_e32 v162, s29, v241
	ds_read_b128 v[134:137], v146
	ds_read_b128 v[138:141], v146 offset:1024
	ds_read_b128 v[142:145], v146 offset:2048
	ds_read_b128 v[146:149], v146 offset:3072
	ds_read_b128 v[150:153], v162
	ds_read_b128 v[154:157], v162 offset:1024
	ds_read_b128 v[158:161], v162 offset:2048
	ds_read_b128 v[162:165], v162 offset:3072
	s_add_u32 s8, s8, s26
	s_addc_u32 s9, s9, s27
	s_mov_b32 m0, s39
	ds_read_b128 v[166:169], v0 offset:32768
	ds_read_b128 v[170:173], v0 offset:33792
	ds_read_b128 v[174:177], v0 offset:34816
	ds_read_b128 v[178:181], v0 offset:35840
	ds_read_b128 v[182:185], v0 offset:36864
	ds_read_b128 v[186:189], v0 offset:37888
	ds_read_b128 v[190:193], v0 offset:38912
	ds_read_b128 v[210:213], v0 offset:39936
	global_load_lds_dwordx4 v218, s[8:9]
	s_mov_b32 m0, s91
	s_nop 0
	global_load_lds_dwordx4 v220, s[8:9]
	s_waitcnt vmcnt(8)
	s_waitcnt lgkmcnt(0)
	s_barrier
; #define PG8_LDA(dst, b, h) do { _Pragma("unroll") for (int m = 0; m < 4; ++m) _Pragma("unroll") for (int k = 0; k < 2; ++k) dst[m][k] = *(const LAS bf16x8*)(lds + PG8_SA(b, h) + aoff + m * 2048 + k * 1024); } while (0)
; #define PG8_MMA(ai, bj, At, Bt) do { __builtin_amdgcn_s_setprio(1); _Pragma("unroll") for (int m = 0; m < 4; ++m) _Pragma("unroll") for (int n = 0; n < 2; ++n) _Pragma("unroll") for (int k = 0; k < 2; ++k) \
;         acc[ai][bj][m][n] = __builtin_amdgcn_mfma_f32_16x16x32_bf16(Bt[n][k], At[m][k], acc[ai][bj][m][n], 0, 0, 0); __builtin_amdgcn_s_setprio(0); } while (0)
; #define PG8_WAIT_V(n) asm volatile("s_waitcnt vmcnt(" #n ")" ::: "memory")
; #define PG8_WAIT_L(n) asm volatile("s_waitcnt lgkmcnt(" #n ")" ::: "memory")
; #define PG8_BAR __builtin_amdgcn_s_barrier()
; #define PG8_SCHED __builtin_amdgcn_sched_barrier(0)
; #define PG8_STA(bufoff, gbase, ld) PG8_STAGE(bufoff, gbase, RA0 * (unsigned)(ld) + CC0, RA1 * (unsigned)(ld) + CC1)
; #define PG8_STB(bufoff, gbase, ld) PG8_STAGE(bufoff, gbase, RB0 * (unsigned)(ld) + CC0, RB1 * (unsigned)(ld) + CC1)
; __device__ __forceinline__ void gemm_phase(LAS unsigned char* lds, const Sched& S, const Epi& E) {
;     ...
;             PG8_WAIT_V(8); PG8_WAIT_L(0); PG8_BAR; PG8_MMA(0, 0, At, B0); PG8_MMA(0, 1, At, B1); PG8_BAR; PG8_SCHED;
;             PG8_LDA(At, 1, 1); PG8_STB(PG8_SB(1, 0), b3, xldb); PG8_STB(PG8_SB(1, 1), b3 + xhB, xldb); PG8_STA(PG8_SA(1, 0), a3, xlda);
;             PG8_WAIT_V(8); PG8_WAIT_L(0); PG8_BAR; PG8_MMA(1, 0, At, B0); PG8_MMA(1, 1, At, B1); PG8_BAR; PG8_SCHED;
;         }
	s_nop 0
	s_waitcnt lgkmcnt(0)
	v_mfma_f32_16x16x32_bf16 v[126:129], v[134:137], v[166:169], v[126:129]
	v_mfma_f32_16x16x32_bf16 v[122:125], v[142:145], v[166:169], v[122:125]
	v_mfma_f32_16x16x32_bf16 v[110:113], v[134:137], v[174:177], v[110:113]
	v_mfma_f32_16x16x32_bf16 v[106:109], v[142:145], v[174:177], v[106:109]
	v_mfma_f32_16x16x32_bf16 v[98:101], v[134:137], v[182:185], v[98:101]
	v_mfma_f32_16x16x32_bf16 v[90:93], v[142:145], v[182:185], v[90:93]
	v_mfma_f32_16x16x32_bf16 v[82:85], v[134:137], v[190:193], v[82:85]
	v_mfma_f32_16x16x32_bf16 v[74:77], v[142:145], v[190:193], v[74:77]
	v_mfma_f32_16x16x32_bf16 v[126:129], v[138:141], v[170:173], v[126:129]
	v_mfma_f32_16x16x32_bf16 v[122:125], v[146:149], v[170:173], v[122:125]
	v_mfma_f32_16x16x32_bf16 v[110:113], v[138:141], v[178:181], v[110:113]
	v_mfma_f32_16x16x32_bf16 v[106:109], v[146:149], v[178:181], v[106:109]
	v_mfma_f32_16x16x32_bf16 v[98:101], v[138:141], v[186:189], v[98:101]
	v_mfma_f32_16x16x32_bf16 v[90:93], v[146:149], v[186:189], v[90:93]
	v_mfma_f32_16x16x32_bf16 v[82:85], v[138:141], v[210:213], v[82:85]
	v_mfma_f32_16x16x32_bf16 v[74:77], v[146:149], v[210:213], v[74:77]
	s_nop 0
	s_nop 0
	v_mfma_f32_16x16x32_bf16 v[118:121], v[150:153], v[166:169], v[118:121]
	v_mfma_f32_16x16x32_bf16 v[114:117], v[158:161], v[166:169], v[114:117]
	v_mfma_f32_16x16x32_bf16 v[102:105], v[150:153], v[174:177], v[102:105]
	v_mfma_f32_16x16x32_bf16 v[94:97], v[158:161], v[174:177], v[94:97]
	v_mfma_f32_16x16x32_bf16 v[86:89], v[150:153], v[182:185], v[86:89]
	v_mfma_f32_16x16x32_bf16 v[78:81], v[158:161], v[182:185], v[78:81]
	v_mfma_f32_16x16x32_bf16 v[70:73], v[150:153], v[190:193], v[70:73]
	v_mfma_f32_16x16x32_bf16 v[66:69], v[158:161], v[190:193], v[66:69]
	v_mfma_f32_16x16x32_bf16 v[118:121], v[154:157], v[170:173], v[118:121]
	v_mfma_f32_16x16x32_bf16 v[114:117], v[162:165], v[170:173], v[114:117]
	v_mfma_f32_16x16x32_bf16 v[102:105], v[154:157], v[178:181], v[102:105]
	v_mfma_f32_16x16x32_bf16 v[94:97], v[162:165], v[178:181], v[94:97]
	v_mfma_f32_16x16x32_bf16 v[86:89], v[154:157], v[186:189], v[86:89]
	v_mfma_f32_16x16x32_bf16 v[78:81], v[162:165], v[186:189], v[78:81]
	v_mfma_f32_16x16x32_bf16 v[70:73], v[154:157], v[210:213], v[70:73]
	v_mfma_f32_16x16x32_bf16 v[66:69], v[162:165], v[210:213], v[66:69]
	s_nop 0
	s_barrier
	s_add_i32 s8, s28, s25
	v_lshl_add_u64 v[218:219], v[222:223], 0, s[52:53]
	s_mov_b32 m0, s8
	ds_read_b128 v[166:169], v0 offset:49152
	ds_read_b128 v[170:173], v0 offset:50176
	ds_read_b128 v[174:177], v0 offset:51200
	ds_read_b128 v[178:181], v0 offset:52224
	ds_read_b128 v[182:185], v0 offset:53248
	ds_read_b128 v[186:189], v0 offset:54272
	ds_read_b128 v[190:193], v0 offset:55296
	ds_read_b128 v[210:213], v0 offset:56320
	global_load_lds_dwordx4 v[218:219], off
	v_lshl_add_u64 v[218:219], v[224:225], 0, s[52:53]
	s_add_i32 m0, s8, 0x2000
	s_add_i32 s8, s29, s25
	global_load_lds_dwordx4 v[218:219], off
	v_lshl_add_u64 v[214:215], v[214:215], 0, s[52:53]
	s_mov_b32 m0, s8
	s_nop 0
	global_load_lds_dwordx4 v[214:215], off
	v_lshl_add_u64 v[214:215], v[216:217], 0, s[52:53]
	s_add_i32 m0, s8, 0x2000
	s_nop 0
	global_load_lds_dwordx4 v[214:215], off
	v_lshl_add_u64 v[214:215], v[226:227], 0, s[52:53]
	s_mov_b32 m0, s90
	s_nop 0
	global_load_lds_dwordx4 v[214:215], off
	v_lshl_add_u64 v[214:215], v[228:229], 0, s[52:53]
	s_mov_b32 m0, s73
	s_nop 0
	global_load_lds_dwordx4 v[214:215], off
	s_nop 0
	s_waitcnt vmcnt(8)
	s_waitcnt lgkmcnt(0)
	s_barrier
	s_nop 0
	s_waitcnt lgkmcnt(0)
	v_mfma_f32_16x16x32_bf16 v[62:65], v[134:137], v[166:169], v[62:65]
	v_mfma_f32_16x16x32_bf16 v[58:61], v[142:145], v[166:169], v[58:61]
	v_mfma_f32_16x16x32_bf16 v[46:49], v[134:137], v[174:177], v[46:49]
	v_mfma_f32_16x16x32_bf16 v[42:45], v[142:145], v[174:177], v[42:45]
	v_mfma_f32_16x16x32_bf16 v[30:33], v[134:137], v[182:185], v[30:33]
	v_mfma_f32_16x16x32_bf16 v[26:29], v[142:145], v[182:185], v[26:29]
	v_mfma_f32_16x16x32_bf16 v[14:17], v[134:137], v[190:193], v[14:17]
	v_mfma_f32_16x16x32_bf16 v[10:13], v[142:145], v[190:193], v[10:13]
	v_mfma_f32_16x16x32_bf16 v[62:65], v[138:141], v[170:173], v[62:65]
	v_mfma_f32_16x16x32_bf16 v[58:61], v[146:149], v[170:173], v[58:61]
	v_mfma_f32_16x16x32_bf16 v[46:49], v[138:141], v[178:181], v[46:49]
	v_mfma_f32_16x16x32_bf16 v[42:45], v[146:149], v[178:181], v[42:45]
	v_mfma_f32_16x16x32_bf16 v[30:33], v[138:141], v[186:189], v[30:33]
	v_mfma_f32_16x16x32_bf16 v[26:29], v[146:149], v[186:189], v[26:29]
	v_mfma_f32_16x16x32_bf16 v[14:17], v[138:141], v[210:213], v[14:17]
	v_mfma_f32_16x16x32_bf16 v[10:13], v[146:149], v[210:213], v[10:13]
	s_nop 0
	s_nop 0
	v_mfma_f32_16x16x32_bf16 v[54:57], v[150:153], v[166:169], v[54:57]
	v_mfma_f32_16x16x32_bf16 v[50:53], v[158:161], v[166:169], v[50:53]
	v_mfma_f32_16x16x32_bf16 v[38:41], v[150:153], v[174:177], v[38:41]
	v_mfma_f32_16x16x32_bf16 v[34:37], v[158:161], v[174:177], v[34:37]
	v_mfma_f32_16x16x32_bf16 v[22:25], v[150:153], v[182:185], v[22:25]
	v_mfma_f32_16x16x32_bf16 v[18:21], v[158:161], v[182:185], v[18:21]
	v_mfma_f32_16x16x32_bf16 v[6:9], v[150:153], v[190:193], v[6:9]
	v_mfma_f32_16x16x32_bf16 v[2:5], v[158:161], v[190:193], v[2:5]
	v_mfma_f32_16x16x32_bf16 v[54:57], v[154:157], v[170:173], v[54:57]
	v_mfma_f32_16x16x32_bf16 v[50:53], v[162:165], v[170:173], v[50:53]
	v_mfma_f32_16x16x32_bf16 v[38:41], v[154:157], v[178:181], v[38:41]
	v_mfma_f32_16x16x32_bf16 v[34:37], v[162:165], v[178:181], v[34:37]
	v_mfma_f32_16x16x32_bf16 v[22:25], v[154:157], v[186:189], v[22:25]
	v_mfma_f32_16x16x32_bf16 v[18:21], v[162:165], v[186:189], v[18:21]
	v_mfma_f32_16x16x32_bf16 v[6:9], v[154:157], v[210:213], v[6:9]
	v_mfma_f32_16x16x32_bf16 v[2:5], v[162:165], v[210:213], v[2:5]
	s_nop 0
	s_barrier
	s_add_u32 vcc_lo, vcc_lo, 0x100
	s_addc_u32 vcc_hi, vcc_hi, 0
	s_add_u32 s2, s2, 0x100
	s_addc_u32 s72, s72, 0
	s_cmp_ge_i32 s24, s68
	s_mov_b32 s8, s24
	s_cbranch_scc0 .LBB0_263
	s_nop 0
	s_mov_b32 s92, s3
	s_movk_i32 s93, 0x3fff
	s_movk_i32 s3, 0x2000
	s_and_b64 vcc, exec, s[44:45]
	s_cbranch_vccz .LBB0_266
; #define PG8_LDA(dst, b, h) do { _Pragma("unroll") for (int m = 0; m < 4; ++m) _Pragma("unroll") for (int k = 0; k < 2; ++k) dst[m][k] = *(const LAS bf16x8*)(lds + PG8_SA(b, h) + aoff + m * 2048 + k * 1024); } while (0)
; #define PG8_LDB(dst, b, h) do { _Pragma("unroll") for (int n = 0; n < 2; ++n) _Pragma("unroll") for (int k = 0; k < 2; ++k) dst[n][k] = *(const LAS bf16x8*)(lds + PG8_SB(b, h) + boff + n * 2048 + k * 1024); } while (0)
; #define PG8_MMA(ai, bj, At, Bt) do { __builtin_amdgcn_s_setprio(1); _Pragma("unroll") for (int m = 0; m < 4; ++m) _Pragma("unroll") for (int n = 0; n < 2; ++n) _Pragma("unroll") for (int k = 0; k < 2; ++k) \
;         acc[ai][bj][m][n] = __builtin_amdgcn_mfma_f32_16x16x32_bf16(Bt[n][k], At[m][k], acc[ai][bj][m][n], 0, 0, 0); __builtin_amdgcn_s_setprio(0); } while (0)
; #define PG8_WAIT_V(n) asm volatile("s_waitcnt vmcnt(" #n ")" ::: "memory")
; #define PG8_WAIT_L(n) asm volatile("s_waitcnt lgkmcnt(" #n ")" ::: "memory")
; #define PG8_BAR __builtin_amdgcn_s_barrier()
; #define PG8_SCHED __builtin_amdgcn_sched_barrier(0)
; #define PG8_STA(bufoff, gbase, ld) PG8_STAGE(bufoff, gbase, RA0 * (unsigned)(ld) + CC0, RA1 * (unsigned)(ld) + CC1)
; __device__ __forceinline__ void gemm_phase(LAS unsigned char* lds, const Sched& S, const Epi& E) {
;     ...
;         if (!has_next) {
;             const char* a1 = cA + (size_t)(nt - 1) * kstep;
;             PG8_LDB(B0, 0, 0); PG8_LDB(B1, 0, 1); PG8_SCHED; PG8_LDA(At, 0, 0); PG8_STA(PG8_SA(1, 1), a1 + hA, lda);
;             PG8_WAIT_V(8); PG8_WAIT_L(0); PG8_BAR; PG8_MMA(0, 0, At, B0); PG8_MMA(0, 1, At, B1); PG8_BAR; PG8_SCHED;
;             PG8_LDA(At, 0, 1);
;             PG8_WAIT_V(2); PG8_WAIT_L(0); PG8_BAR; PG8_MMA(1, 0, At, B0); PG8_MMA(1, 1, At, B1); PG8_BAR; PG8_SCHED;
.LBB0_265:
	v_add_u32_e32 v0, 0, v241
	v_add_u32_e32 v142, 0x10000, v0
	v_add_u32_e32 v158, 0x14000, v0
	s_waitcnt lgkmcnt(0)
	ds_read_b128 v[130:133], v142
	ds_read_b128 v[134:137], v142 offset:1024
	ds_read_b128 v[138:141], v142 offset:2048
	ds_read_b128 v[142:145], v142 offset:3072
	ds_read_b128 v[146:149], v158
	ds_read_b128 v[150:153], v158 offset:1024
	ds_read_b128 v[154:157], v158 offset:2048
	ds_read_b128 v[158:161], v158 offset:3072
	s_ashr_i32 s61, s60, 31
	s_lshl_b64 s[8:9], s[60:61], 7
	s_add_u32 s2, s96, s8
	s_addc_u32 s8, s97, s9
	s_add_u32 s2, s2, s66
	s_addc_u32 s9, s8, s67
	s_add_u32 s8, s2, 0xffffff80
	v_add_u32_e32 v212, 0, v240
	s_addc_u32 s9, s9, -1
	v_mad_u64_u32 v[210:211], s[26:27], s20, v235, v[194:195]
	s_add_i32 m0, s34, 0xc000
	ds_read_b128 v[162:165], v212
	ds_read_b128 v[166:169], v212 offset:1024
	ds_read_b128 v[170:173], v212 offset:2048
	ds_read_b128 v[174:177], v212 offset:3072
	ds_read_b128 v[178:181], v212 offset:4096
	ds_read_b128 v[182:185], v212 offset:5120
	ds_read_b128 v[186:189], v212 offset:6144
	ds_read_b128 v[190:193], v212 offset:7168
	global_load_lds_dwordx4 v210, s[8:9]
	v_mad_u64_u32 v[210:211], s[20:21], s20, v236, v[196:197]
	s_add_i32 m0, s34, 0xe000
	s_nop 0
	global_load_lds_dwordx4 v210, s[8:9]
	s_waitcnt vmcnt(8)
	s_waitcnt lgkmcnt(0)
	s_barrier
	s_nop 0
	s_waitcnt lgkmcnt(0)
	v_mfma_f32_16x16x32_bf16 v[126:129], v[130:133], v[162:165], v[126:129]
	v_mfma_f32_16x16x32_bf16 v[122:125], v[138:141], v[162:165], v[122:125]
	v_mfma_f32_16x16x32_bf16 v[110:113], v[130:133], v[170:173], v[110:113]
	v_mfma_f32_16x16x32_bf16 v[106:109], v[138:141], v[170:173], v[106:109]
	v_mfma_f32_16x16x32_bf16 v[98:101], v[130:133], v[178:181], v[98:101]
	v_mfma_f32_16x16x32_bf16 v[90:93], v[138:141], v[178:181], v[90:93]
	v_mfma_f32_16x16x32_bf16 v[82:85], v[130:133], v[186:189], v[82:85]
	v_mfma_f32_16x16x32_bf16 v[74:77], v[138:141], v[186:189], v[74:77]
	v_mfma_f32_16x16x32_bf16 v[126:129], v[134:137], v[166:169], v[126:129]
	v_mfma_f32_16x16x32_bf16 v[122:125], v[142:145], v[166:169], v[122:125]
	v_mfma_f32_16x16x32_bf16 v[110:113], v[134:137], v[174:177], v[110:113]
	v_mfma_f32_16x16x32_bf16 v[106:109], v[142:145], v[174:177], v[106:109]
	v_mfma_f32_16x16x32_bf16 v[98:101], v[134:137], v[182:185], v[98:101]
	v_mfma_f32_16x16x32_bf16 v[90:93], v[142:145], v[182:185], v[90:93]
	v_mfma_f32_16x16x32_bf16 v[82:85], v[134:137], v[190:193], v[82:85]
	v_mfma_f32_16x16x32_bf16 v[74:77], v[142:145], v[190:193], v[74:77]
	s_nop 0
	s_nop 0
	v_mfma_f32_16x16x32_bf16 v[118:121], v[146:149], v[162:165], v[118:121]
	v_mfma_f32_16x16x32_bf16 v[114:117], v[154:157], v[162:165], v[114:117]
	v_mfma_f32_16x16x32_bf16 v[102:105], v[146:149], v[170:173], v[102:105]
	v_mfma_f32_16x16x32_bf16 v[94:97], v[154:157], v[170:173], v[94:97]
	v_mfma_f32_16x16x32_bf16 v[86:89], v[146:149], v[178:181], v[86:89]
	v_mfma_f32_16x16x32_bf16 v[78:81], v[154:157], v[178:181], v[78:81]
	v_mfma_f32_16x16x32_bf16 v[70:73], v[146:149], v[186:189], v[70:73]
	v_mfma_f32_16x16x32_bf16 v[66:69], v[154:157], v[186:189], v[66:69]
	v_mfma_f32_16x16x32_bf16 v[118:121], v[150:153], v[166:169], v[118:121]
	v_mfma_f32_16x16x32_bf16 v[114:117], v[158:161], v[166:169], v[114:117]
	v_mfma_f32_16x16x32_bf16 v[102:105], v[150:153], v[174:177], v[102:105]
	v_mfma_f32_16x16x32_bf16 v[94:97], v[158:161], v[174:177], v[94:97]
	v_mfma_f32_16x16x32_bf16 v[86:89], v[150:153], v[182:185], v[86:89]
	v_mfma_f32_16x16x32_bf16 v[78:81], v[158:161], v[182:185], v[78:81]
	v_mfma_f32_16x16x32_bf16 v[70:73], v[150:153], v[190:193], v[70:73]
	v_mfma_f32_16x16x32_bf16 v[66:69], v[158:161], v[190:193], v[66:69]
	s_nop 0
	s_barrier
	ds_read_b128 v[162:165], v212 offset:16384
	ds_read_b128 v[166:169], v212 offset:17408
	ds_read_b128 v[170:173], v212 offset:18432
	ds_read_b128 v[174:177], v212 offset:19456
	ds_read_b128 v[178:181], v212 offset:20480
	ds_read_b128 v[182:185], v212 offset:21504
	ds_read_b128 v[186:189], v212 offset:22528
	ds_read_b128 v[190:193], v212 offset:23552
	s_waitcnt vmcnt(2)
	s_waitcnt lgkmcnt(0)
	s_barrier
	s_nop 0
	s_waitcnt lgkmcnt(0)
	v_mfma_f32_16x16x32_bf16 v[62:65], v[130:133], v[162:165], v[62:65]
	v_mfma_f32_16x16x32_bf16 v[58:61], v[138:141], v[162:165], v[58:61]
	v_mfma_f32_16x16x32_bf16 v[46:49], v[130:133], v[170:173], v[46:49]
	v_mfma_f32_16x16x32_bf16 v[42:45], v[138:141], v[170:173], v[42:45]
	v_mfma_f32_16x16x32_bf16 v[30:33], v[130:133], v[178:181], v[30:33]
	v_mfma_f32_16x16x32_bf16 v[26:29], v[138:141], v[178:181], v[26:29]
	v_mfma_f32_16x16x32_bf16 v[14:17], v[130:133], v[186:189], v[14:17]
	v_mfma_f32_16x16x32_bf16 v[10:13], v[138:141], v[186:189], v[10:13]
	v_mfma_f32_16x16x32_bf16 v[62:65], v[134:137], v[166:169], v[62:65]
	v_mfma_f32_16x16x32_bf16 v[58:61], v[142:145], v[166:169], v[58:61]
	v_mfma_f32_16x16x32_bf16 v[46:49], v[134:137], v[174:177], v[46:49]
	v_mfma_f32_16x16x32_bf16 v[42:45], v[142:145], v[174:177], v[42:45]
	v_mfma_f32_16x16x32_bf16 v[30:33], v[134:137], v[182:185], v[30:33]
	v_mfma_f32_16x16x32_bf16 v[26:29], v[142:145], v[182:185], v[26:29]
	v_mfma_f32_16x16x32_bf16 v[14:17], v[134:137], v[190:193], v[14:17]
	v_mfma_f32_16x16x32_bf16 v[10:13], v[142:145], v[190:193], v[10:13]
	s_nop 0
	s_nop 0
	v_mfma_f32_16x16x32_bf16 v[54:57], v[146:149], v[162:165], v[54:57]
	v_mfma_f32_16x16x32_bf16 v[50:53], v[154:157], v[162:165], v[50:53]
	v_mfma_f32_16x16x32_bf16 v[38:41], v[146:149], v[170:173], v[38:41]
	v_mfma_f32_16x16x32_bf16 v[34:37], v[154:157], v[170:173], v[34:37]
	v_mfma_f32_16x16x32_bf16 v[22:25], v[146:149], v[178:181], v[22:25]
	v_mfma_f32_16x16x32_bf16 v[18:21], v[154:157], v[178:181], v[18:21]
	v_mfma_f32_16x16x32_bf16 v[6:9], v[146:149], v[186:189], v[6:9]
	v_mfma_f32_16x16x32_bf16 v[2:5], v[154:157], v[186:189], v[2:5]
	v_mfma_f32_16x16x32_bf16 v[54:57], v[150:153], v[166:169], v[54:57]
	v_mfma_f32_16x16x32_bf16 v[50:53], v[158:161], v[166:169], v[50:53]
	v_mfma_f32_16x16x32_bf16 v[38:41], v[150:153], v[174:177], v[38:41]
	v_mfma_f32_16x16x32_bf16 v[34:37], v[158:161], v[174:177], v[34:37]
	v_mfma_f32_16x16x32_bf16 v[22:25], v[150:153], v[182:185], v[22:25]
	v_mfma_f32_16x16x32_bf16 v[18:21], v[158:161], v[182:185], v[18:21]
	v_mfma_f32_16x16x32_bf16 v[6:9], v[150:153], v[190:193], v[6:9]
	v_mfma_f32_16x16x32_bf16 v[2:5], v[158:161], v[190:193], v[2:5]
	s_nop 0
	s_barrier
; #define PG8_LDA(dst, b, h) do { _Pragma("unroll") for (int m = 0; m < 4; ++m) _Pragma("unroll") for (int k = 0; k < 2; ++k) dst[m][k] = *(const LAS bf16x8*)(lds + PG8_SA(b, h) + aoff + m * 2048 + k * 1024); } while (0)
; #define PG8_LDB(dst, b, h) do { _Pragma("unroll") for (int n = 0; n < 2; ++n) _Pragma("unroll") for (int k = 0; k < 2; ++k) dst[n][k] = *(const LAS bf16x8*)(lds + PG8_SB(b, h) + boff + n * 2048 + k * 1024); } while (0)
; #define PG8_MMA(ai, bj, At, Bt) do { __builtin_amdgcn_s_setprio(1); _Pragma("unroll") for (int m = 0; m < 4; ++m) _Pragma("unroll") for (int n = 0; n < 2; ++n) _Pragma("unroll") for (int k = 0; k < 2; ++k) \
;         acc[ai][bj][m][n] = __builtin_amdgcn_mfma_f32_16x16x32_bf16(Bt[n][k], At[m][k], acc[ai][bj][m][n], 0, 0, 0); __builtin_amdgcn_s_setprio(0); } while (0)
; #define PG8_WAIT_V(n) asm volatile("s_waitcnt vmcnt(" #n ")" ::: "memory")
; #define PG8_WAIT_L(n) asm volatile("s_waitcnt lgkmcnt(" #n ")" ::: "memory")
; #define PG8_BAR __builtin_amdgcn_s_barrier()
; #define PG8_SCHED __builtin_amdgcn_sched_barrier(0)
; __device__ __forceinline__ void gemm_phase(LAS unsigned char* lds, const Sched& S, const Epi& E) {
;     ...
;             PG8_LDB(B0, 1, 0); PG8_LDB(B1, 1, 1); PG8_SCHED; PG8_LDA(At, 1, 0);
;             PG8_WAIT_V(0); PG8_WAIT_L(0); PG8_BAR; PG8_MMA(0, 0, At, B0); PG8_MMA(0, 1, At, B1); PG8_BAR; PG8_SCHED;
;             PG8_LDA(At, 1, 1);
;             PG8_WAIT_L(0); PG8_BAR; PG8_MMA(1, 0, At, B0); PG8_MMA(1, 1, At, B1); PG8_BAR; PG8_SCHED;
;         }
;         if (wr == 0) PG8_BAR;
;         epi_run(E, acc, cur, wr, wc, fr, fq);
	v_add_u32_e32 v142, 0x18000, v0
	v_add_u32_e32 v0, 0x1c000, v0
	ds_read_b128 v[130:133], v142
	ds_read_b128 v[134:137], v142 offset:1024
	ds_read_b128 v[138:141], v142 offset:2048
	ds_read_b128 v[142:145], v142 offset:3072
	ds_read_b128 v[146:149], v0
	ds_read_b128 v[150:153], v0 offset:1024
	ds_read_b128 v[154:157], v0 offset:2048
	ds_read_b128 v[158:161], v0 offset:3072
	ds_read_b128 v[162:165], v212 offset:32768
	ds_read_b128 v[166:169], v212 offset:33792
	ds_read_b128 v[170:173], v212 offset:34816
	ds_read_b128 v[174:177], v212 offset:35840
	ds_read_b128 v[178:181], v212 offset:36864
	ds_read_b128 v[182:185], v212 offset:37888
	ds_read_b128 v[186:189], v212 offset:38912
	ds_read_b128 v[190:193], v212 offset:39936
	s_waitcnt vmcnt(0)
	s_waitcnt lgkmcnt(0)
	s_barrier
	s_nop 0
	s_waitcnt lgkmcnt(0)
	v_mfma_f32_16x16x32_bf16 v[126:129], v[130:133], v[162:165], v[126:129]
	v_mfma_f32_16x16x32_bf16 v[122:125], v[138:141], v[162:165], v[122:125]
	v_mfma_f32_16x16x32_bf16 v[110:113], v[130:133], v[170:173], v[110:113]
	v_mfma_f32_16x16x32_bf16 v[106:109], v[138:141], v[170:173], v[106:109]
	v_mfma_f32_16x16x32_bf16 v[98:101], v[130:133], v[178:181], v[98:101]
	v_mfma_f32_16x16x32_bf16 v[90:93], v[138:141], v[178:181], v[90:93]
	v_mfma_f32_16x16x32_bf16 v[82:85], v[130:133], v[186:189], v[82:85]
	v_mfma_f32_16x16x32_bf16 v[74:77], v[138:141], v[186:189], v[74:77]
	v_mfma_f32_16x16x32_bf16 v[126:129], v[134:137], v[166:169], v[126:129]
	v_mfma_f32_16x16x32_bf16 v[122:125], v[142:145], v[166:169], v[122:125]
	v_mfma_f32_16x16x32_bf16 v[110:113], v[134:137], v[174:177], v[110:113]
	v_mfma_f32_16x16x32_bf16 v[106:109], v[142:145], v[174:177], v[106:109]
	v_mfma_f32_16x16x32_bf16 v[98:101], v[134:137], v[182:185], v[98:101]
	v_mfma_f32_16x16x32_bf16 v[90:93], v[142:145], v[182:185], v[90:93]
	v_mfma_f32_16x16x32_bf16 v[82:85], v[134:137], v[190:193], v[82:85]
	v_mfma_f32_16x16x32_bf16 v[74:77], v[142:145], v[190:193], v[74:77]
	s_nop 0
	s_nop 0
	v_mfma_f32_16x16x32_bf16 v[118:121], v[146:149], v[162:165], v[118:121]
	v_mfma_f32_16x16x32_bf16 v[114:117], v[154:157], v[162:165], v[114:117]
	v_mfma_f32_16x16x32_bf16 v[102:105], v[146:149], v[170:173], v[102:105]
	v_mfma_f32_16x16x32_bf16 v[94:97], v[154:157], v[170:173], v[94:97]
	v_mfma_f32_16x16x32_bf16 v[86:89], v[146:149], v[178:181], v[86:89]
	v_mfma_f32_16x16x32_bf16 v[78:81], v[154:157], v[178:181], v[78:81]
	v_mfma_f32_16x16x32_bf16 v[70:73], v[146:149], v[186:189], v[70:73]
	v_mfma_f32_16x16x32_bf16 v[66:69], v[154:157], v[186:189], v[66:69]
	v_mfma_f32_16x16x32_bf16 v[118:121], v[150:153], v[166:169], v[118:121]
	v_mfma_f32_16x16x32_bf16 v[114:117], v[158:161], v[166:169], v[114:117]
	v_mfma_f32_16x16x32_bf16 v[102:105], v[150:153], v[174:177], v[102:105]
	v_mfma_f32_16x16x32_bf16 v[94:97], v[158:161], v[174:177], v[94:97]
	v_mfma_f32_16x16x32_bf16 v[86:89], v[150:153], v[182:185], v[86:89]
	v_mfma_f32_16x16x32_bf16 v[78:81], v[158:161], v[182:185], v[78:81]
	v_mfma_f32_16x16x32_bf16 v[70:73], v[150:153], v[190:193], v[70:73]
	v_mfma_f32_16x16x32_bf16 v[66:69], v[158:161], v[190:193], v[66:69]
	s_nop 0
	s_barrier
	ds_read_b128 v[162:165], v212 offset:49152
	ds_read_b128 v[166:169], v212 offset:50176
	ds_read_b128 v[170:173], v212 offset:51200
	ds_read_b128 v[174:177], v212 offset:52224
	ds_read_b128 v[178:181], v212 offset:53248
	ds_read_b128 v[182:185], v212 offset:54272
	ds_read_b128 v[186:189], v212 offset:55296
	ds_read_b128 v[190:193], v212 offset:56320
	s_waitcnt lgkmcnt(0)
	s_barrier
	s_nop 0
	s_waitcnt lgkmcnt(0)
	v_mfma_f32_16x16x32_bf16 v[62:65], v[130:133], v[162:165], v[62:65]
	v_mfma_f32_16x16x32_bf16 v[58:61], v[138:141], v[162:165], v[58:61]
	v_mfma_f32_16x16x32_bf16 v[46:49], v[130:133], v[170:173], v[46:49]
	v_mfma_f32_16x16x32_bf16 v[42:45], v[138:141], v[170:173], v[42:45]
	v_mfma_f32_16x16x32_bf16 v[30:33], v[130:133], v[178:181], v[30:33]
	v_mfma_f32_16x16x32_bf16 v[26:29], v[138:141], v[178:181], v[26:29]
	v_mfma_f32_16x16x32_bf16 v[14:17], v[130:133], v[186:189], v[14:17]
	v_mfma_f32_16x16x32_bf16 v[10:13], v[138:141], v[186:189], v[10:13]
	v_mfma_f32_16x16x32_bf16 v[62:65], v[134:137], v[166:169], v[62:65]
	v_mfma_f32_16x16x32_bf16 v[58:61], v[142:145], v[166:169], v[58:61]
	v_mfma_f32_16x16x32_bf16 v[46:49], v[134:137], v[174:177], v[46:49]
	v_mfma_f32_16x16x32_bf16 v[42:45], v[142:145], v[174:177], v[42:45]
	v_mfma_f32_16x16x32_bf16 v[30:33], v[134:137], v[182:185], v[30:33]
	v_mfma_f32_16x16x32_bf16 v[26:29], v[142:145], v[182:185], v[26:29]
	v_mfma_f32_16x16x32_bf16 v[14:17], v[134:137], v[190:193], v[14:17]
	v_mfma_f32_16x16x32_bf16 v[10:13], v[142:145], v[190:193], v[10:13]
	s_nop 0
	s_nop 0
	v_mfma_f32_16x16x32_bf16 v[54:57], v[146:149], v[162:165], v[54:57]
	v_mfma_f32_16x16x32_bf16 v[50:53], v[154:157], v[162:165], v[50:53]
	v_mfma_f32_16x16x32_bf16 v[38:41], v[146:149], v[170:173], v[38:41]
	v_mfma_f32_16x16x32_bf16 v[34:37], v[154:157], v[170:173], v[34:37]
	v_mfma_f32_16x16x32_bf16 v[22:25], v[146:149], v[178:181], v[22:25]
	v_mfma_f32_16x16x32_bf16 v[18:21], v[154:157], v[178:181], v[18:21]
	v_mfma_f32_16x16x32_bf16 v[6:9], v[146:149], v[186:189], v[6:9]
	v_mfma_f32_16x16x32_bf16 v[2:5], v[154:157], v[186:189], v[2:5]
	v_mfma_f32_16x16x32_bf16 v[54:57], v[150:153], v[166:169], v[54:57]
	v_mfma_f32_16x16x32_bf16 v[50:53], v[158:161], v[166:169], v[50:53]
	v_mfma_f32_16x16x32_bf16 v[38:41], v[150:153], v[174:177], v[38:41]
	v_mfma_f32_16x16x32_bf16 v[34:37], v[158:161], v[174:177], v[34:37]
	v_mfma_f32_16x16x32_bf16 v[22:25], v[150:153], v[182:185], v[22:25]
	v_mfma_f32_16x16x32_bf16 v[18:21], v[158:161], v[182:185], v[18:21]
	v_mfma_f32_16x16x32_bf16 v[6:9], v[150:153], v[190:193], v[6:9]
	v_mfma_f32_16x16x32_bf16 v[2:5], v[158:161], v[190:193], v[2:5]
	s_nop 0
	s_barrier
.LBB0_266:
	s_setprio 0
	s_andn2_b64 vcc, exec, s[4:5]
	s_cbranch_vccz .LBB0_272
	v_lshl_add_u32 v210, s95, 8, v239
	s_cmp_lt_i32 s83, 3
	v_lshl_or_b32 v212, s23, 8, v242
	s_cbranch_scc1 .LBB0_273

; #define PG8_BAR __builtin_amdgcn_s_barrier()
; __device__ __forceinline__ void gemm_phase(LAS unsigned char* lds, const Sched& S, const Epi& E) {
;     ...
;         if (wr == 0) PG8_BAR;
;         epi_run(E, acc, cur, wr, wc, fr, fq);
;         if (!has_next) break;
.Lmy_tramp7:
	s_branch .LBB0_7
.Lmy_tramp456:
	s_branch .LBB0_456
